# FFN-in GEMM load segments: s_sleep 3 in the 2-DMA phases, s_sleep 1 in the 6-DMA phases
# speedup vs baseline: 1.0077x; 1.0033x over previous
; template <class Epi, class Sched, bool ALIGN_EPI = false, bool SP2 = false>
; __device__ __forceinline__ void gemm_phase(PG8_LAS unsigned char* lds, const Gemm g, const Sched& S, const Epi& E) {
;     ...
;         const bool has_next = S.next(ui + 1, nxt);
;         const char* nA = has_next ? (const char*)g.A + (size_t)nxt.pm * tstepA : cA; const char* nB = has_next ? (const char*)g.Bt + (size_t)nxt.pn * tstepB : cB;
.LBB0_477:
	s_ashr_i32 s27, s26, 31
	s_lshl_b64 s[2:3], s[26:27], 15
	v_readlane_b32 s10, v255, 15
	s_add_u32 s28, s10, s2
	v_readlane_b32 s2, v255, 16
	s_addc_u32 s29, s2, s3
	s_ashr_i32 s25, s24, 31
	s_lshl_b64 s[2:3], s[24:25], 19
	s_add_u32 s30, s19, s2
	s_addc_u32 s31, s22, s3
	s_add_u32 s44, s34, 0x800000
	s_addc_u32 s45, s35, 0
	s_add_u32 s42, s34, 0xc00000
	s_addc_u32 s43, s35, 0
	s_add_i32 s61, 0, 0x10000
	s_and_b64 s[2:3], s[40:41], exec
	s_cselect_b32 s25, s29, s35
	s_cselect_b32 s27, s28, s34
	s_add_i32 s97, 0, 0x14000
	v_add_u32_e32 v142, s61, v97
	v_add_u32_e32 v143, s97, v97
	ds_read_b128 v[0:3], v142
	ds_read_b128 v[4:7], v142 offset:1024
	ds_read_b128 v[8:11], v142 offset:2048
	ds_read_b128 v[12:15], v142 offset:3072
	ds_read_b128 v[16:19], v143
	s_waitcnt lgkmcnt(0)
	ds_read_b128 v[20:23], v143 offset:1024
	ds_read_b128 v[24:27], v143 offset:2048
	ds_read_b128 v[28:31], v143 offset:3072
	s_and_b64 s[2:3], s[40:41], exec
	s_cselect_b32 s57, s31, s1
	s_cselect_b32 s58, s30, s0
	s_add_u32 s2, s34, 0x404000
	s_addc_u32 s3, s35, 0
	s_add_i32 s59, s23, 0xc000
	v_lshl_add_u64 v[64:65], s[2:3], 0, v[130:131]
	s_mov_b32 m0, s59
	s_add_i32 s60, s23, 0xe000
	ds_read_b128 v[32:35], v156
	ds_read_b128 v[36:39], v156 offset:1024
	ds_read_b128 v[40:43], v156 offset:2048
	ds_read_b128 v[44:47], v156 offset:3072
	ds_read_b128 v[48:51], v156 offset:4096
	ds_read_b128 v[52:55], v156 offset:5120
	ds_read_b128 v[56:59], v156 offset:6144
	ds_read_b128 v[60:63], v156 offset:7168
	global_load_lds_dwordx4 v[64:65], off
	v_lshl_add_u64 v[64:65], s[2:3], 0, v[134:135]
	s_mov_b32 m0, s60
	s_nop 0
	global_load_lds_dwordx4 v[64:65], off
	s_sleep 3
	s_waitcnt vmcnt(8)
	s_waitcnt lgkmcnt(0)
	s_barrier
	s_setprio 1
	s_waitcnt lgkmcnt(0)
	v_mfma_f32_16x16x32_bf16 v[88:91], v[0:3], v[56:59], 0
	v_mfma_f32_16x16x32_bf16 v[64:67], v[0:3], v[32:35], 0
	v_mfma_f32_16x16x32_bf16 v[68:71], v[8:11], v[32:35], 0
	v_mfma_f32_16x16x32_bf16 v[72:75], v[0:3], v[40:43], 0
	v_mfma_f32_16x16x32_bf16 v[76:79], v[8:11], v[40:43], 0
	v_mfma_f32_16x16x32_bf16 v[80:83], v[0:3], v[48:51], 0
	v_mfma_f32_16x16x32_bf16 v[84:87], v[8:11], v[48:51], 0
	v_mfma_f32_16x16x32_bf16 v[92:95], v[4:7], v[60:63], v[88:91]
	v_mfma_f32_16x16x32_bf16 v[88:91], v[8:11], v[56:59], 0
	v_mfma_f32_16x16x32_bf16 v[64:67], v[4:7], v[36:39], v[64:67]
	v_mfma_f32_16x16x32_bf16 v[68:71], v[12:15], v[36:39], v[68:71]
	v_mfma_f32_16x16x32_bf16 v[72:75], v[4:7], v[44:47], v[72:75]
	v_mfma_f32_16x16x32_bf16 v[76:79], v[12:15], v[44:47], v[76:79]
	v_mfma_f32_16x16x32_bf16 v[80:83], v[4:7], v[52:55], v[80:83]
	v_mfma_f32_16x16x32_bf16 v[84:87], v[12:15], v[52:55], v[84:87]
	v_mfma_f32_16x16x32_bf16 v[102:105], v[12:15], v[60:63], v[88:91]
	s_setprio 0
	s_setprio 1
	v_mfma_f32_16x16x32_bf16 v[88:91], v[16:19], v[32:35], 0
	v_mfma_f32_16x16x32_bf16 v[32:35], v[24:27], v[32:35], 0
	v_mfma_f32_16x16x32_bf16 v[110:113], v[20:23], v[36:39], v[88:91]
	v_mfma_f32_16x16x32_bf16 v[32:35], v[28:31], v[36:39], v[32:35]
	v_mfma_f32_16x16x32_bf16 v[36:39], v[16:19], v[40:43], 0
	v_mfma_f32_16x16x32_bf16 v[40:43], v[24:27], v[40:43], 0
	v_mfma_f32_16x16x32_bf16 v[36:39], v[20:23], v[44:47], v[36:39]
	v_mfma_f32_16x16x32_bf16 v[40:43], v[28:31], v[44:47], v[40:43]
	v_mfma_f32_16x16x32_bf16 v[44:47], v[16:19], v[48:51], 0
	v_mfma_f32_16x16x32_bf16 v[48:51], v[24:27], v[48:51], 0
	v_mfma_f32_16x16x32_bf16 v[44:47], v[20:23], v[52:55], v[44:47]
	v_mfma_f32_16x16x32_bf16 v[48:51], v[28:31], v[52:55], v[48:51]
	v_mfma_f32_16x16x32_bf16 v[52:55], v[16:19], v[56:59], 0
	v_mfma_f32_16x16x32_bf16 v[56:59], v[24:27], v[56:59], 0
	v_mfma_f32_16x16x32_bf16 v[52:55], v[20:23], v[60:63], v[52:55]
	v_mfma_f32_16x16x32_bf16 v[56:59], v[28:31], v[60:63], v[56:59]
	s_setprio 0
	s_barrier
	v_lshl_add_u64 v[154:155], s[0:1], 0, v[132:133]
	s_mov_b64 s[2:3], 0x100
	s_add_i32 s61, s61, s9
	v_lshl_add_u64 v[144:145], v[154:155], 0, s[2:3]
	s_mov_b32 m0, s61
	v_lshl_add_u64 v[178:179], s[0:1], 0, v[136:137]
	s_add_i32 s96, s61, 0x2000
	ds_read_b128 v[60:63], v156 offset:16384
	ds_read_b128 v[88:91], v156 offset:17408
	ds_read_b128 v[98:101], v156 offset:18432
	ds_read_b128 v[106:109], v156 offset:19456
	ds_read_b128 v[114:117], v156 offset:20480
	ds_read_b128 v[118:121], v156 offset:21504
	ds_read_b128 v[122:125], v156 offset:22528
	ds_read_b128 v[126:129], v156 offset:23552
	global_load_lds_dwordx4 v[144:145], off
	v_lshl_add_u64 v[144:145], v[178:179], 0, s[2:3]
	s_add_u32 s2, s0, 0x40100
	s_mov_b32 m0, s96
	s_addc_u32 s3, s1, 0
	s_add_i32 s97, s97, s9
	global_load_lds_dwordx4 v[144:145], off
	v_lshl_add_u64 v[144:145], s[2:3], 0, v[132:133]
	s_mov_b32 m0, s97
	s_add_i32 s98, s97, 0x2000
	global_load_lds_dwordx4 v[144:145], off
	v_lshl_add_u64 v[144:145], s[2:3], 0, v[136:137]
	s_mov_b32 m0, s98
	s_nop 0
	global_load_lds_dwordx4 v[144:145], off
	v_lshl_add_u64 v[144:145], s[44:45], 0, v[130:131]
	s_mov_b32 m0, s23
	s_nop 0
	global_load_lds_dwordx4 v[144:145], off
	v_lshl_add_u64 v[144:145], s[44:45], 0, v[134:135]
	s_mov_b32 m0, s39
	s_nop 0
	global_load_lds_dwordx4 v[144:145], off
	s_sleep 1
	s_waitcnt vmcnt(8)
	s_waitcnt lgkmcnt(0)
	s_barrier
	s_setprio 1
	s_waitcnt lgkmcnt(0)
	v_mfma_f32_16x16x32_bf16 v[144:147], v[0:3], v[60:63], 0
	v_mfma_f32_16x16x32_bf16 v[158:161], v[0:3], v[98:101], 0
	v_mfma_f32_16x16x32_bf16 v[166:169], v[0:3], v[114:117], 0
	v_mfma_f32_16x16x32_bf16 v[0:3], v[0:3], v[122:125], 0
	v_mfma_f32_16x16x32_bf16 v[146:149], v[4:7], v[88:91], v[144:147]
	v_mfma_f32_16x16x32_bf16 v[158:161], v[4:7], v[106:109], v[158:161]
	v_mfma_f32_16x16x32_bf16 v[166:169], v[4:7], v[118:121], v[166:169]
	v_mfma_f32_16x16x32_bf16 v[0:3], v[4:7], v[126:129], v[0:3]
	v_mfma_f32_16x16x32_bf16 v[4:7], v[8:11], v[122:125], 0
	v_mfma_f32_16x16x32_bf16 v[150:153], v[8:11], v[60:63], 0
	v_mfma_f32_16x16x32_bf16 v[162:165], v[8:11], v[98:101], 0
	v_mfma_f32_16x16x32_bf16 v[170:173], v[8:11], v[114:117], 0
	v_mfma_f32_16x16x32_bf16 v[4:7], v[12:15], v[126:129], v[4:7]
	v_mfma_f32_16x16x32_bf16 v[150:153], v[12:15], v[88:91], v[150:153]
	v_mfma_f32_16x16x32_bf16 v[162:165], v[12:15], v[106:109], v[162:165]
	v_mfma_f32_16x16x32_bf16 v[170:173], v[12:15], v[118:121], v[170:173]
	s_setprio 0
	s_setprio 1
	v_mfma_f32_16x16x32_bf16 v[8:11], v[16:19], v[60:63], 0
	v_mfma_f32_16x16x32_bf16 v[12:15], v[20:23], v[88:91], v[8:11]
	v_mfma_f32_16x16x32_bf16 v[8:11], v[24:27], v[60:63], 0
	v_mfma_f32_16x16x32_bf16 v[174:177], v[28:31], v[88:91], v[8:11]
	v_mfma_f32_16x16x32_bf16 v[8:11], v[16:19], v[98:101], 0
	v_mfma_f32_16x16x32_bf16 v[188:191], v[20:23], v[106:109], v[8:11]
	v_mfma_f32_16x16x32_bf16 v[8:11], v[24:27], v[98:101], 0
	v_mfma_f32_16x16x32_bf16 v[192:195], v[28:31], v[106:109], v[8:11]
	v_mfma_f32_16x16x32_bf16 v[8:11], v[16:19], v[114:117], 0
	v_mfma_f32_16x16x32_bf16 v[196:199], v[20:23], v[118:121], v[8:11]
	v_mfma_f32_16x16x32_bf16 v[8:11], v[24:27], v[114:117], 0
	v_mfma_f32_16x16x32_bf16 v[200:203], v[28:31], v[118:121], v[8:11]
	v_mfma_f32_16x16x32_bf16 v[8:11], v[16:19], v[122:125], 0
	v_mfma_f32_16x16x32_bf16 v[204:207], v[20:23], v[126:129], v[8:11]
	v_mfma_f32_16x16x32_bf16 v[8:11], v[24:27], v[122:125], 0
	v_mfma_f32_16x16x32_bf16 v[208:211], v[28:31], v[126:129], v[8:11]
	s_setprio 0
	s_barrier
	s_add_i32 s99, 0, 0x18000
	s_add_i32 vcc_hi, 0, 0x1c000
	v_add_u32_e32 v144, s99, v97
	v_add_u32_e32 v145, vcc_hi, v97
	s_nop 0
	ds_read_b128 v[8:11], v144
	ds_read_b128 v[20:23], v144 offset:1024
	ds_read_b128 v[28:31], v144 offset:2048
	ds_read_b128 v[212:215], v144 offset:3072
	ds_read_b128 v[216:219], v145
	ds_read_b128 v[220:223], v145 offset:1024
	ds_read_b128 v[234:237], v145 offset:2048
	ds_read_b128 v[238:241], v145 offset:3072
	s_add_u32 s2, s34, 0x804000
	s_addc_u32 s3, s35, 0
	s_mov_b32 m0, s46
	v_lshl_add_u64 v[60:61], s[2:3], 0, v[130:131]
	ds_read_b128 v[16:19], v156 offset:32768
	ds_read_b128 v[24:27], v156 offset:33792
	ds_read_b128 v[242:245], v156 offset:34816
	ds_read_b128 v[246:249], v156 offset:35840
	ds_read_b128 v[228:231], v156 offset:36864
	ds_read_b128 v[180:183], v156 offset:37888
	ds_read_b128 v[184:187], v156 offset:38912
	ds_read_b128 v[224:227], v156 offset:39936
	global_load_lds_dwordx4 v[60:61], off
	v_lshl_add_u64 v[60:61], s[2:3], 0, v[134:135]
	s_mov_b32 m0, s47
	s_nop 0
	global_load_lds_dwordx4 v[60:61], off
	s_sleep 3
	s_waitcnt vmcnt(8)
	s_waitcnt lgkmcnt(0)
	s_barrier
	s_setprio 1
	s_waitcnt lgkmcnt(0)
	v_mfma_f32_16x16x32_bf16 v[60:63], v[8:11], v[16:19], v[64:67]
	v_mfma_f32_16x16x32_bf16 v[122:125], v[20:23], v[24:27], v[60:63]
	v_mfma_f32_16x16x32_bf16 v[60:63], v[28:31], v[16:19], v[68:71]
	v_mfma_f32_16x16x32_bf16 v[114:117], v[212:215], v[24:27], v[60:63]
	v_mfma_f32_16x16x32_bf16 v[60:63], v[8:11], v[242:245], v[72:75]
	v_mfma_f32_16x16x32_bf16 v[106:109], v[20:23], v[246:249], v[60:63]
	v_mfma_f32_16x16x32_bf16 v[60:63], v[28:31], v[242:245], v[76:79]
	v_mfma_f32_16x16x32_bf16 v[98:101], v[212:215], v[246:249], v[60:63]
	v_mfma_f32_16x16x32_bf16 v[60:63], v[8:11], v[228:231], v[80:83]
	v_mfma_f32_16x16x32_bf16 v[88:91], v[20:23], v[180:183], v[60:63]
	v_mfma_f32_16x16x32_bf16 v[60:63], v[28:31], v[228:231], v[84:87]
	v_mfma_f32_16x16x32_bf16 v[80:83], v[212:215], v[180:183], v[60:63]
	v_mfma_f32_16x16x32_bf16 v[60:63], v[8:11], v[184:187], v[92:95]
	v_mfma_f32_16x16x32_bf16 v[72:75], v[20:23], v[224:227], v[60:63]
	v_mfma_f32_16x16x32_bf16 v[60:63], v[28:31], v[184:187], v[102:105]
	v_mfma_f32_16x16x32_bf16 v[60:63], v[212:215], v[224:227], v[60:63]
	s_setprio 0
	s_setprio 1
	v_mfma_f32_16x16x32_bf16 v[64:67], v[216:219], v[16:19], v[110:113]
	v_mfma_f32_16x16x32_bf16 v[16:19], v[234:237], v[16:19], v[32:35]
	v_mfma_f32_16x16x32_bf16 v[118:121], v[238:241], v[24:27], v[16:19]
	v_mfma_f32_16x16x32_bf16 v[16:19], v[216:219], v[242:245], v[36:39]
	v_mfma_f32_16x16x32_bf16 v[110:113], v[220:223], v[246:249], v[16:19]
	v_mfma_f32_16x16x32_bf16 v[16:19], v[234:237], v[242:245], v[40:43]
	v_mfma_f32_16x16x32_bf16 v[102:105], v[238:241], v[246:249], v[16:19]
	v_mfma_f32_16x16x32_bf16 v[16:19], v[216:219], v[228:231], v[44:47]
	v_mfma_f32_16x16x32_bf16 v[92:95], v[220:223], v[180:183], v[16:19]
	v_mfma_f32_16x16x32_bf16 v[16:19], v[234:237], v[228:231], v[48:51]
	v_mfma_f32_16x16x32_bf16 v[84:87], v[238:241], v[180:183], v[16:19]
	v_mfma_f32_16x16x32_bf16 v[16:19], v[216:219], v[184:187], v[52:55]
	v_mfma_f32_16x16x32_bf16 v[76:79], v[220:223], v[224:227], v[16:19]
	v_mfma_f32_16x16x32_bf16 v[16:19], v[234:237], v[184:187], v[56:59]
	v_mfma_f32_16x16x32_bf16 v[126:129], v[220:223], v[24:27], v[64:67]
	v_mfma_f32_16x16x32_bf16 v[68:71], v[238:241], v[224:227], v[16:19]
	s_setprio 0
	s_barrier
; template <class Epi, class Sched, bool ALIGN_EPI = false, bool SP2 = false>
; __device__ __forceinline__ void gemm_phase(PG8_LAS unsigned char* lds, const Gemm g, const Sched& S, const Epi& E) {
;     ...
;         if constexpr (Epi::PEEL) {
;             const char* a1 = cA + kstepA; const char* a2 = cA + 2 * kstepA; const char* b2 = cB + 2 * kstepB; const char* a3 = a2 + kstepA; const char* b3 = b2 + kstepB;
;             PG8_ITER(8);
;         }
;         for (int t = (Epi::PEEL ? 2 : 0); t < nt; t += 2) {
;             const bool last = (t == nt - 2);
;             const char* a1 = cA + (size_t)(t + 1) * kstepA;
;             const char* a2 = last ? nA : cA + (size_t)(t + 2) * kstepA; const char* b2 = last ? nB : cB + (size_t)(t + 2) * kstepB;
;             const char* a3 = a2 + kstepA; const char* b3 = b2 + kstepB;
;             PG8_ITER(8);
	s_mov_b64 s[2:3], 0x180
	s_add_i32 s99, s99, s9
	s_nop 1
	v_lshl_add_u64 v[16:17], v[154:155], 0, s[2:3]
	s_mov_b32 m0, s99
	s_add_i32 vcc_lo, s99, 0x2000
	ds_read_b128 v[36:39], v156 offset:49152
	ds_read_b128 v[44:47], v156 offset:50176
	ds_read_b128 v[180:183], v156 offset:51200
	ds_read_b128 v[184:187], v156 offset:52224
	ds_read_b128 v[224:227], v156 offset:53248
	ds_read_b128 v[228:231], v156 offset:54272
	ds_read_b128 v[242:245], v156 offset:55296
	ds_read_b128 v[246:249], v156 offset:56320
	global_load_lds_dwordx4 v[16:17], off
	v_lshl_add_u64 v[16:17], v[178:179], 0, s[2:3]
	s_add_u32 s2, s0, 0x40180
	s_mov_b32 m0, vcc_lo
	s_addc_u32 s3, s1, 0
	s_add_i32 vcc_hi, vcc_hi, s9
	global_load_lds_dwordx4 v[16:17], off
	v_lshl_add_u64 v[16:17], s[2:3], 0, v[132:133]
	s_mov_b32 m0, vcc_hi
	s_add_i32 s38, vcc_hi, 0x2000
	global_load_lds_dwordx4 v[16:17], off
	v_lshl_add_u64 v[16:17], s[2:3], 0, v[136:137]
	s_mov_b32 m0, s38
	s_nop 0
	global_load_lds_dwordx4 v[16:17], off
	v_lshl_add_u64 v[16:17], s[42:43], 0, v[130:131]
	s_mov_b32 m0, s49
	s_nop 0
	global_load_lds_dwordx4 v[16:17], off
	v_lshl_add_u64 v[16:17], s[42:43], 0, v[134:135]
	s_mov_b32 m0, s50
	s_nop 0
	global_load_lds_dwordx4 v[16:17], off
	s_sleep 1
	s_waitcnt vmcnt(8)
	s_waitcnt lgkmcnt(0)
	s_barrier
	s_setprio 1
	s_waitcnt lgkmcnt(0)
	v_mfma_f32_16x16x32_bf16 v[16:19], v[8:11], v[36:39], v[146:149]
	v_mfma_f32_16x16x32_bf16 v[56:59], v[20:23], v[44:47], v[16:19]
	v_mfma_f32_16x16x32_bf16 v[16:19], v[28:31], v[36:39], v[150:153]
	v_mfma_f32_16x16x32_bf16 v[48:51], v[212:215], v[44:47], v[16:19]
	v_mfma_f32_16x16x32_bf16 v[16:19], v[8:11], v[180:183], v[158:161]
	v_mfma_f32_16x16x32_bf16 v[40:43], v[20:23], v[184:187], v[16:19]
	v_mfma_f32_16x16x32_bf16 v[16:19], v[28:31], v[180:183], v[162:165]
	v_mfma_f32_16x16x32_bf16 v[32:35], v[212:215], v[184:187], v[16:19]
	v_mfma_f32_16x16x32_bf16 v[16:19], v[8:11], v[224:227], v[166:169]
	v_mfma_f32_16x16x32_bf16 v[0:3], v[8:11], v[242:245], v[0:3]
	v_mfma_f32_16x16x32_bf16 v[24:27], v[20:23], v[228:231], v[16:19]
	v_mfma_f32_16x16x32_bf16 v[16:19], v[28:31], v[224:227], v[170:173]
	v_mfma_f32_16x16x32_bf16 v[8:11], v[20:23], v[246:249], v[0:3]
	v_mfma_f32_16x16x32_bf16 v[0:3], v[28:31], v[242:245], v[4:7]
	v_mfma_f32_16x16x32_bf16 v[16:19], v[212:215], v[228:231], v[16:19]
	v_mfma_f32_16x16x32_bf16 v[0:3], v[212:215], v[246:249], v[0:3]
	s_setprio 0
	s_setprio 1
	v_mfma_f32_16x16x32_bf16 v[4:7], v[216:219], v[36:39], v[12:15]
	v_mfma_f32_16x16x32_bf16 v[64:67], v[220:223], v[44:47], v[4:7]
	v_mfma_f32_16x16x32_bf16 v[4:7], v[234:237], v[36:39], v[174:177]
	v_mfma_f32_16x16x32_bf16 v[52:55], v[238:241], v[44:47], v[4:7]
	v_mfma_f32_16x16x32_bf16 v[4:7], v[216:219], v[180:183], v[188:191]
	v_mfma_f32_16x16x32_bf16 v[44:47], v[220:223], v[184:187], v[4:7]
	v_mfma_f32_16x16x32_bf16 v[4:7], v[234:237], v[180:183], v[192:195]
	v_mfma_f32_16x16x32_bf16 v[36:39], v[238:241], v[184:187], v[4:7]
	v_mfma_f32_16x16x32_bf16 v[4:7], v[216:219], v[224:227], v[196:199]
	v_mfma_f32_16x16x32_bf16 v[28:31], v[220:223], v[228:231], v[4:7]
	v_mfma_f32_16x16x32_bf16 v[4:7], v[234:237], v[224:227], v[200:203]
	v_mfma_f32_16x16x32_bf16 v[20:23], v[238:241], v[228:231], v[4:7]
	v_mfma_f32_16x16x32_bf16 v[4:7], v[216:219], v[242:245], v[204:207]
	v_mfma_f32_16x16x32_bf16 v[12:15], v[220:223], v[246:249], v[4:7]
	v_mfma_f32_16x16x32_bf16 v[4:7], v[234:237], v[242:245], v[208:211]
	v_mfma_f32_16x16x32_bf16 v[4:7], v[238:241], v[246:249], v[4:7]
	s_setprio 0
	s_barrier
	s_add_u32 s3, s0, 0x200
	s_addc_u32 s2, s1, 0
	s_add_u32 s0, s34, 0xc04000
	s_addc_u32 s1, s35, 0
	s_mov_b32 s18, 0
.LBB0_478:
	ds_read_b128 v[146:149], v142
	ds_read_b128 v[150:153], v142 offset:1024
	ds_read_b128 v[158:161], v142 offset:2048
	ds_read_b128 v[162:165], v142 offset:3072
	ds_read_b128 v[166:169], v143
	ds_read_b128 v[170:173], v143 offset:1024
	ds_read_b128 v[174:177], v143 offset:2048
	ds_read_b128 v[180:183], v143 offset:3072
	s_add_u32 s10, s0, 0x3fc000
	s_addc_u32 s11, s1, 0
	s_cmp_eq_u32 s18, 12
	s_cselect_b32 s44, s27, s10
	s_cselect_b32 s45, s25, s11
	s_cselect_b32 s42, s58, s3
	s_cselect_b32 s43, s57, s2
	s_add_u32 s34, s44, 0x400000
	s_addc_u32 s35, s45, 0
	s_mov_b32 m0, s59
	v_lshl_add_u64 v[154:155], s[0:1], 0, v[140:141]
	ds_read_b128 v[184:187], v156
	ds_read_b128 v[188:191], v156 offset:1024
	ds_read_b128 v[192:195], v156 offset:2048
	ds_read_b128 v[196:199], v156 offset:3072
	ds_read_b128 v[200:203], v156 offset:4096
	ds_read_b128 v[204:207], v156 offset:5120
	ds_read_b128 v[208:211], v156 offset:6144
	ds_read_b128 v[212:215], v156 offset:7168
	global_load_lds_dwordx4 v[154:155], off
	v_lshl_add_u64 v[154:155], s[0:1], 0, v[138:139]
	s_mov_b32 m0, s60
	s_nop 0
	global_load_lds_dwordx4 v[154:155], off
	s_sleep 3
	s_waitcnt vmcnt(8)
	s_waitcnt lgkmcnt(0)
	s_barrier
	s_setprio 1
	s_waitcnt lgkmcnt(0)
	v_mfma_f32_16x16x32_bf16 v[122:125], v[146:149], v[184:187], v[122:125]
	v_mfma_f32_16x16x32_bf16 v[114:117], v[158:161], v[184:187], v[114:117]
	v_mfma_f32_16x16x32_bf16 v[106:109], v[146:149], v[192:195], v[106:109]
	v_mfma_f32_16x16x32_bf16 v[98:101], v[158:161], v[192:195], v[98:101]
	v_mfma_f32_16x16x32_bf16 v[88:91], v[146:149], v[200:203], v[88:91]
	v_mfma_f32_16x16x32_bf16 v[80:83], v[158:161], v[200:203], v[80:83]
	v_mfma_f32_16x16x32_bf16 v[72:75], v[146:149], v[208:211], v[72:75]
	v_mfma_f32_16x16x32_bf16 v[60:63], v[158:161], v[208:211], v[60:63]
	v_mfma_f32_16x16x32_bf16 v[122:125], v[150:153], v[188:191], v[122:125]
	v_mfma_f32_16x16x32_bf16 v[114:117], v[162:165], v[188:191], v[114:117]
	v_mfma_f32_16x16x32_bf16 v[106:109], v[150:153], v[196:199], v[106:109]
	v_mfma_f32_16x16x32_bf16 v[98:101], v[162:165], v[196:199], v[98:101]
	v_mfma_f32_16x16x32_bf16 v[88:91], v[150:153], v[204:207], v[88:91]
	v_mfma_f32_16x16x32_bf16 v[80:83], v[162:165], v[204:207], v[80:83]
	v_mfma_f32_16x16x32_bf16 v[72:75], v[150:153], v[212:215], v[72:75]
	v_mfma_f32_16x16x32_bf16 v[60:63], v[162:165], v[212:215], v[60:63]
	s_setprio 0
	s_setprio 1
	v_mfma_f32_16x16x32_bf16 v[126:129], v[166:169], v[184:187], v[126:129]
	v_mfma_f32_16x16x32_bf16 v[118:121], v[174:177], v[184:187], v[118:121]
	v_mfma_f32_16x16x32_bf16 v[110:113], v[166:169], v[192:195], v[110:113]
	v_mfma_f32_16x16x32_bf16 v[102:105], v[174:177], v[192:195], v[102:105]
	v_mfma_f32_16x16x32_bf16 v[92:95], v[166:169], v[200:203], v[92:95]
	v_mfma_f32_16x16x32_bf16 v[84:87], v[174:177], v[200:203], v[84:87]
	v_mfma_f32_16x16x32_bf16 v[76:79], v[166:169], v[208:211], v[76:79]
	v_mfma_f32_16x16x32_bf16 v[68:71], v[174:177], v[208:211], v[68:71]
	v_mfma_f32_16x16x32_bf16 v[126:129], v[170:173], v[188:191], v[126:129]
	v_mfma_f32_16x16x32_bf16 v[118:121], v[180:183], v[188:191], v[118:121]
	v_mfma_f32_16x16x32_bf16 v[110:113], v[170:173], v[196:199], v[110:113]
	v_mfma_f32_16x16x32_bf16 v[102:105], v[180:183], v[196:199], v[102:105]
	v_mfma_f32_16x16x32_bf16 v[92:95], v[170:173], v[204:207], v[92:95]
	v_mfma_f32_16x16x32_bf16 v[84:87], v[180:183], v[204:207], v[84:87]
	v_mfma_f32_16x16x32_bf16 v[76:79], v[170:173], v[212:215], v[76:79]
	v_mfma_f32_16x16x32_bf16 v[68:71], v[180:183], v[212:215], v[68:71]
	s_setprio 0
	s_barrier
	s_mov_b32 m0, s61
	v_lshl_add_u64 v[154:155], s[42:43], 0, v[132:133]
	s_add_u32 s10, s42, 0x40000
	ds_read_b128 v[184:187], v156 offset:16384
	ds_read_b128 v[188:191], v156 offset:17408
	ds_read_b128 v[192:195], v156 offset:18432
	ds_read_b128 v[196:199], v156 offset:19456
	ds_read_b128 v[200:203], v156 offset:20480
	ds_read_b128 v[204:207], v156 offset:21504
	ds_read_b128 v[208:211], v156 offset:22528
	ds_read_b128 v[212:215], v156 offset:23552
	global_load_lds_dwordx4 v[154:155], off
	v_lshl_add_u64 v[178:179], s[42:43], 0, v[136:137]
	s_mov_b32 m0, s96
	s_addc_u32 s11, s43, 0
	global_load_lds_dwordx4 v[178:179], off
	v_lshl_add_u64 v[216:217], s[10:11], 0, v[132:133]
	s_mov_b32 m0, s97
	s_nop 0
	global_load_lds_dwordx4 v[216:217], off
	v_lshl_add_u64 v[216:217], s[10:11], 0, v[136:137]
	s_mov_b32 m0, s98
	s_nop 0
	global_load_lds_dwordx4 v[216:217], off
	v_lshl_add_u64 v[216:217], s[44:45], 0, v[130:131]
	s_mov_b32 m0, s23
	s_nop 0
	global_load_lds_dwordx4 v[216:217], off
	v_lshl_add_u64 v[216:217], s[44:45], 0, v[134:135]
	s_mov_b32 m0, s39
	s_nop 0
	global_load_lds_dwordx4 v[216:217], off
	s_sleep 1
	s_waitcnt vmcnt(8)
	s_waitcnt lgkmcnt(0)
	s_barrier
	s_setprio 1
	s_waitcnt lgkmcnt(0)
	v_mfma_f32_16x16x32_bf16 v[56:59], v[146:149], v[184:187], v[56:59]
	v_mfma_f32_16x16x32_bf16 v[48:51], v[158:161], v[184:187], v[48:51]
	v_mfma_f32_16x16x32_bf16 v[40:43], v[146:149], v[192:195], v[40:43]
	v_mfma_f32_16x16x32_bf16 v[32:35], v[158:161], v[192:195], v[32:35]
	v_mfma_f32_16x16x32_bf16 v[24:27], v[146:149], v[200:203], v[24:27]
	v_mfma_f32_16x16x32_bf16 v[16:19], v[158:161], v[200:203], v[16:19]
	v_mfma_f32_16x16x32_bf16 v[8:11], v[146:149], v[208:211], v[8:11]
	v_mfma_f32_16x16x32_bf16 v[0:3], v[158:161], v[208:211], v[0:3]
	v_mfma_f32_16x16x32_bf16 v[56:59], v[150:153], v[188:191], v[56:59]
	v_mfma_f32_16x16x32_bf16 v[48:51], v[162:165], v[188:191], v[48:51]
	v_mfma_f32_16x16x32_bf16 v[40:43], v[150:153], v[196:199], v[40:43]
	v_mfma_f32_16x16x32_bf16 v[32:35], v[162:165], v[196:199], v[32:35]
	v_mfma_f32_16x16x32_bf16 v[24:27], v[150:153], v[204:207], v[24:27]
	v_mfma_f32_16x16x32_bf16 v[16:19], v[162:165], v[204:207], v[16:19]
	v_mfma_f32_16x16x32_bf16 v[8:11], v[150:153], v[212:215], v[8:11]
	v_mfma_f32_16x16x32_bf16 v[0:3], v[162:165], v[212:215], v[0:3]
	s_setprio 0
	s_setprio 1
	v_mfma_f32_16x16x32_bf16 v[64:67], v[166:169], v[184:187], v[64:67]
	v_mfma_f32_16x16x32_bf16 v[52:55], v[174:177], v[184:187], v[52:55]
	v_mfma_f32_16x16x32_bf16 v[44:47], v[166:169], v[192:195], v[44:47]
	v_mfma_f32_16x16x32_bf16 v[36:39], v[174:177], v[192:195], v[36:39]
	v_mfma_f32_16x16x32_bf16 v[28:31], v[166:169], v[200:203], v[28:31]
	v_mfma_f32_16x16x32_bf16 v[20:23], v[174:177], v[200:203], v[20:23]
	v_mfma_f32_16x16x32_bf16 v[12:15], v[166:169], v[208:211], v[12:15]
	v_mfma_f32_16x16x32_bf16 v[4:7], v[174:177], v[208:211], v[4:7]
	v_mfma_f32_16x16x32_bf16 v[64:67], v[170:173], v[188:191], v[64:67]
	v_mfma_f32_16x16x32_bf16 v[52:55], v[180:183], v[188:191], v[52:55]
	v_mfma_f32_16x16x32_bf16 v[44:47], v[170:173], v[196:199], v[44:47]
	v_mfma_f32_16x16x32_bf16 v[36:39], v[180:183], v[196:199], v[36:39]
	v_mfma_f32_16x16x32_bf16 v[28:31], v[170:173], v[204:207], v[28:31]
	v_mfma_f32_16x16x32_bf16 v[20:23], v[180:183], v[204:207], v[20:23]
	v_mfma_f32_16x16x32_bf16 v[12:15], v[170:173], v[212:215], v[12:15]
	v_mfma_f32_16x16x32_bf16 v[4:7], v[180:183], v[212:215], v[4:7]
	s_setprio 0
	s_barrier
	ds_read_b128 v[146:149], v144
	ds_read_b128 v[150:153], v144 offset:1024
	ds_read_b128 v[158:161], v144 offset:2048
	ds_read_b128 v[162:165], v144 offset:3072
	ds_read_b128 v[166:169], v145
	ds_read_b128 v[170:173], v145 offset:1024
	ds_read_b128 v[174:177], v145 offset:2048
	ds_read_b128 v[180:183], v145 offset:3072
	s_add_u32 s10, s44, 0x4000
	s_addc_u32 s11, s45, 0
	s_mov_b32 m0, s46
	v_lshl_add_u64 v[216:217], s[10:11], 0, v[130:131]
	ds_read_b128 v[184:187], v156 offset:32768
	ds_read_b128 v[188:191], v156 offset:33792
	ds_read_b128 v[192:195], v156 offset:34816
	ds_read_b128 v[196:199], v156 offset:35840
	ds_read_b128 v[200:203], v156 offset:36864
	ds_read_b128 v[204:207], v156 offset:37888
	ds_read_b128 v[208:211], v156 offset:38912
	ds_read_b128 v[212:215], v156 offset:39936
	global_load_lds_dwordx4 v[216:217], off
	v_lshl_add_u64 v[216:217], s[10:11], 0, v[134:135]
	s_mov_b32 m0, s47
	s_nop 0
	global_load_lds_dwordx4 v[216:217], off
	s_sleep 3
	s_waitcnt vmcnt(8)
	s_waitcnt lgkmcnt(0)
	s_barrier
	s_setprio 1
	s_waitcnt lgkmcnt(0)
	v_mfma_f32_16x16x32_bf16 v[122:125], v[146:149], v[184:187], v[122:125]
	v_mfma_f32_16x16x32_bf16 v[114:117], v[158:161], v[184:187], v[114:117]
	v_mfma_f32_16x16x32_bf16 v[106:109], v[146:149], v[192:195], v[106:109]
	v_mfma_f32_16x16x32_bf16 v[98:101], v[158:161], v[192:195], v[98:101]
	v_mfma_f32_16x16x32_bf16 v[88:91], v[146:149], v[200:203], v[88:91]
	v_mfma_f32_16x16x32_bf16 v[80:83], v[158:161], v[200:203], v[80:83]
	v_mfma_f32_16x16x32_bf16 v[72:75], v[146:149], v[208:211], v[72:75]
	v_mfma_f32_16x16x32_bf16 v[60:63], v[158:161], v[208:211], v[60:63]
	v_mfma_f32_16x16x32_bf16 v[122:125], v[150:153], v[188:191], v[122:125]
	v_mfma_f32_16x16x32_bf16 v[114:117], v[162:165], v[188:191], v[114:117]
	v_mfma_f32_16x16x32_bf16 v[106:109], v[150:153], v[196:199], v[106:109]
	v_mfma_f32_16x16x32_bf16 v[98:101], v[162:165], v[196:199], v[98:101]
	v_mfma_f32_16x16x32_bf16 v[88:91], v[150:153], v[204:207], v[88:91]
	v_mfma_f32_16x16x32_bf16 v[80:83], v[162:165], v[204:207], v[80:83]
	v_mfma_f32_16x16x32_bf16 v[72:75], v[150:153], v[212:215], v[72:75]
	v_mfma_f32_16x16x32_bf16 v[60:63], v[162:165], v[212:215], v[60:63]
	s_setprio 0
	s_setprio 1
	v_mfma_f32_16x16x32_bf16 v[126:129], v[166:169], v[184:187], v[126:129]
	v_mfma_f32_16x16x32_bf16 v[118:121], v[174:177], v[184:187], v[118:121]
	v_mfma_f32_16x16x32_bf16 v[110:113], v[166:169], v[192:195], v[110:113]
	v_mfma_f32_16x16x32_bf16 v[102:105], v[174:177], v[192:195], v[102:105]
	v_mfma_f32_16x16x32_bf16 v[92:95], v[166:169], v[200:203], v[92:95]
	v_mfma_f32_16x16x32_bf16 v[84:87], v[174:177], v[200:203], v[84:87]
	v_mfma_f32_16x16x32_bf16 v[76:79], v[166:169], v[208:211], v[76:79]
	v_mfma_f32_16x16x32_bf16 v[68:71], v[174:177], v[208:211], v[68:71]
	v_mfma_f32_16x16x32_bf16 v[126:129], v[170:173], v[188:191], v[126:129]
	v_mfma_f32_16x16x32_bf16 v[118:121], v[180:183], v[188:191], v[118:121]
	v_mfma_f32_16x16x32_bf16 v[110:113], v[170:173], v[196:199], v[110:113]
	v_mfma_f32_16x16x32_bf16 v[102:105], v[180:183], v[196:199], v[102:105]
	v_mfma_f32_16x16x32_bf16 v[92:95], v[170:173], v[204:207], v[92:95]
	v_mfma_f32_16x16x32_bf16 v[84:87], v[180:183], v[204:207], v[84:87]
	v_mfma_f32_16x16x32_bf16 v[76:79], v[170:173], v[212:215], v[76:79]
	v_mfma_f32_16x16x32_bf16 v[68:71], v[180:183], v[212:215], v[68:71]
	s_setprio 0
	s_barrier
; template <class Epi, class Sched, bool ALIGN_EPI = false, bool SP2 = false>
; __device__ __forceinline__ void gemm_phase(PG8_LAS unsigned char* lds, const Gemm g, const Sched& S, const Epi& E) {
;     ...
;         if constexpr (Epi::PEEL) {
;             const char* a1 = cA + kstepA; const char* a2 = cA + 2 * kstepA; const char* b2 = cB + 2 * kstepB; const char* a3 = a2 + kstepA; const char* b3 = b2 + kstepB;
;             PG8_ITER(8);
;         }
;         for (int t = (Epi::PEEL ? 2 : 0); t < nt; t += 2) {
;             const bool last = (t == nt - 2);
;             const char* a1 = cA + (size_t)(t + 1) * kstepA;
;             const char* a2 = last ? nA : cA + (size_t)(t + 2) * kstepA; const char* b2 = last ? nB : cB + (size_t)(t + 2) * kstepB;
;             const char* a3 = a2 + kstepA; const char* b3 = b2 + kstepB;
;             PG8_ITER(8);
;         }
	s_mov_b32 m0, s99
	v_lshl_add_u64 v[154:155], v[154:155], 0, s[36:37]
	s_add_u32 s10, s42, 0x40080
	ds_read_b128 v[184:187], v156 offset:49152
	ds_read_b128 v[188:191], v156 offset:50176
	ds_read_b128 v[192:195], v156 offset:51200
	ds_read_b128 v[196:199], v156 offset:52224
	ds_read_b128 v[200:203], v156 offset:53248
	ds_read_b128 v[204:207], v156 offset:54272
	ds_read_b128 v[208:211], v156 offset:55296
	ds_read_b128 v[212:215], v156 offset:56320
	global_load_lds_dwordx4 v[154:155], off
	v_lshl_add_u64 v[154:155], v[178:179], 0, s[36:37]
	s_mov_b32 m0, vcc_lo
	s_addc_u32 s11, s43, 0
	global_load_lds_dwordx4 v[154:155], off
	v_lshl_add_u64 v[154:155], s[10:11], 0, v[132:133]
	s_mov_b32 m0, vcc_hi
	s_nop 0
	global_load_lds_dwordx4 v[154:155], off
	v_lshl_add_u64 v[154:155], s[10:11], 0, v[136:137]
	s_mov_b32 m0, s38
	s_nop 0
	global_load_lds_dwordx4 v[154:155], off
	v_lshl_add_u64 v[154:155], s[34:35], 0, v[130:131]
	s_mov_b32 m0, s49
	s_nop 0
	global_load_lds_dwordx4 v[154:155], off
	v_lshl_add_u64 v[154:155], s[34:35], 0, v[134:135]
	s_mov_b32 m0, s50
	s_nop 0
	global_load_lds_dwordx4 v[154:155], off
	s_sleep 1
	s_waitcnt vmcnt(8)
	s_waitcnt lgkmcnt(0)
	s_barrier
	s_setprio 1
	s_waitcnt lgkmcnt(0)
	v_mfma_f32_16x16x32_bf16 v[56:59], v[146:149], v[184:187], v[56:59]
	v_mfma_f32_16x16x32_bf16 v[48:51], v[158:161], v[184:187], v[48:51]
	v_mfma_f32_16x16x32_bf16 v[40:43], v[146:149], v[192:195], v[40:43]
	v_mfma_f32_16x16x32_bf16 v[32:35], v[158:161], v[192:195], v[32:35]
	v_mfma_f32_16x16x32_bf16 v[24:27], v[146:149], v[200:203], v[24:27]
	v_mfma_f32_16x16x32_bf16 v[16:19], v[158:161], v[200:203], v[16:19]
	v_mfma_f32_16x16x32_bf16 v[8:11], v[146:149], v[208:211], v[8:11]
	v_mfma_f32_16x16x32_bf16 v[0:3], v[158:161], v[208:211], v[0:3]
	v_mfma_f32_16x16x32_bf16 v[56:59], v[150:153], v[188:191], v[56:59]
	v_mfma_f32_16x16x32_bf16 v[48:51], v[162:165], v[188:191], v[48:51]
	v_mfma_f32_16x16x32_bf16 v[40:43], v[150:153], v[196:199], v[40:43]
	v_mfma_f32_16x16x32_bf16 v[32:35], v[162:165], v[196:199], v[32:35]
	v_mfma_f32_16x16x32_bf16 v[24:27], v[150:153], v[204:207], v[24:27]
	v_mfma_f32_16x16x32_bf16 v[16:19], v[162:165], v[204:207], v[16:19]
	v_mfma_f32_16x16x32_bf16 v[8:11], v[150:153], v[212:215], v[8:11]
	v_mfma_f32_16x16x32_bf16 v[0:3], v[162:165], v[212:215], v[0:3]
	s_setprio 0
	s_setprio 1
	v_mfma_f32_16x16x32_bf16 v[64:67], v[166:169], v[184:187], v[64:67]
	v_mfma_f32_16x16x32_bf16 v[52:55], v[174:177], v[184:187], v[52:55]
	v_mfma_f32_16x16x32_bf16 v[44:47], v[166:169], v[192:195], v[44:47]
	v_mfma_f32_16x16x32_bf16 v[36:39], v[174:177], v[192:195], v[36:39]
	v_mfma_f32_16x16x32_bf16 v[28:31], v[166:169], v[200:203], v[28:31]
	v_mfma_f32_16x16x32_bf16 v[20:23], v[174:177], v[200:203], v[20:23]
	v_mfma_f32_16x16x32_bf16 v[12:15], v[166:169], v[208:211], v[12:15]
	v_mfma_f32_16x16x32_bf16 v[4:7], v[174:177], v[208:211], v[4:7]
	v_mfma_f32_16x16x32_bf16 v[64:67], v[170:173], v[188:191], v[64:67]
	v_mfma_f32_16x16x32_bf16 v[52:55], v[180:183], v[188:191], v[52:55]
	v_mfma_f32_16x16x32_bf16 v[44:47], v[170:173], v[196:199], v[44:47]
	v_mfma_f32_16x16x32_bf16 v[36:39], v[180:183], v[196:199], v[36:39]
	v_mfma_f32_16x16x32_bf16 v[28:31], v[170:173], v[204:207], v[28:31]
	v_mfma_f32_16x16x32_bf16 v[20:23], v[180:183], v[204:207], v[20:23]
	v_mfma_f32_16x16x32_bf16 v[12:15], v[170:173], v[212:215], v[12:15]
	v_mfma_f32_16x16x32_bf16 v[4:7], v[180:183], v[212:215], v[4:7]
	s_setprio 0
	s_barrier
	s_add_i32 s18, s18, 2
	s_add_u32 s3, s3, 0x100
	s_addc_u32 s2, s2, 0
	s_add_u32 s0, s0, 0x800000
	s_addc_u32 s1, s1, 0
	s_cmp_gt_u32 s18, 13
	s_cbranch_scc0 .LBB0_478
	s_and_b64 vcc, exec, s[16:17]
	s_cbranch_vccz .LBB0_481
	s_barrier
